# v3c + P0 adaLN GEMV: 56 loads in flight per wave (was ~7), SiLU staging loads batched; same fma order
# baseline (speedup 1.0000x reference)
.LBB0_11:
	s_or_b64 exec, exec, s[0:1]
	s_lshr_b32 s3, s42, 6
	s_lshl_b32 s0, s53, 3
	s_add_i32 s54, s0, s3
	v_readlane_b32 s4, v253, 8
	v_readlane_b32 s5, v253, 9
	s_cmp_lt_i32 s4, 1
	s_cselect_b64 s[0:1], -1, 0
	s_cmp_gt_i32 s5, 0
	s_cselect_b64 s[4:5], -1, 0
	s_and_b64 s[0:1], s[0:1], s[4:5]
	s_lshl_b32 s4, s3, 9
	s_add_i32 s10, s4, 0
	s_mul_i32 s4, s3, 0x3f00
	s_add_i32 s4, s10, s4
	s_cmpk_lt_i32 s2, 0x100
	v_writelane_b32 v253, s4, 10
	s_cselect_b64 s[4:5], -1, 0
	v_writelane_b32 v253, s4, 11
	s_andn2_b64 vcc, exec, s[0:1]
	s_nop 0
	v_writelane_b32 v253, s5, 12
	s_cbranch_vccnz .LBB0_301
	v_readlane_b32 s8, v253, 0
	s_mov_b64 s[18:19], s[72:73]
	v_readlane_b32 s9, v253, 1
	v_mov_b32_e32 v42, v0
	s_cmpk_gt_i32 s2, 0x8f
	s_nop 0
	v_and_b32_e32 v54, 63, v42
	s_cbranch_scc1 .LBB0_22
	s_movk_i32 s0, 0x1000
	v_cmp_gt_i32_e32 vcc, s0, v42
	s_and_saveexec_b64 s[0:1], vcc
	s_cbranch_execz .LBB0_16
	s_load_dwordx2 s[6:7], s[8:9], 0x8
	v_ashrrev_i32_e32 v43, 31, v42
	v_lshl_add_u32 v3, v42, 2, 0
	s_waitcnt lgkmcnt(0)
	v_lshl_add_u64 v[4:5], v[42:43], 2, s[6:7]
	s_mov_b64 s[6:7], 0x800
	global_load_dword v60, v[4:5], off
	v_lshl_add_u64 v[4:5], v[4:5], 0, s[6:7]
	global_load_dword v61, v[4:5], off
	v_lshl_add_u64 v[4:5], v[4:5], 0, s[6:7]
	global_load_dword v62, v[4:5], off
	v_lshl_add_u64 v[4:5], v[4:5], 0, s[6:7]
	global_load_dword v63, v[4:5], off
	v_lshl_add_u64 v[4:5], v[4:5], 0, s[6:7]
	global_load_dword v64, v[4:5], off
	v_lshl_add_u64 v[4:5], v[4:5], 0, s[6:7]
	global_load_dword v65, v[4:5], off
	v_lshl_add_u64 v[4:5], v[4:5], 0, s[6:7]
	global_load_dword v66, v[4:5], off
	v_lshl_add_u64 v[4:5], v[4:5], 0, s[6:7]
	global_load_dword v67, v[4:5], off
	v_lshl_add_u64 v[4:5], v[4:5], 0, s[6:7]
	s_waitcnt vmcnt(0)
	v_mul_f32_e32 v70, 0xbfb8aa3b, v60
	v_mul_f32_e32 v71, 0xbfb8aa3b, v61
	v_mul_f32_e32 v72, 0xbfb8aa3b, v62
	v_mul_f32_e32 v73, 0xbfb8aa3b, v63
	v_mul_f32_e32 v74, 0xbfb8aa3b, v64
	v_mul_f32_e32 v75, 0xbfb8aa3b, v65
	v_mul_f32_e32 v76, 0xbfb8aa3b, v66
	v_mul_f32_e32 v77, 0xbfb8aa3b, v67
	v_exp_f32_e32 v70, v70
	v_exp_f32_e32 v71, v71
	v_exp_f32_e32 v72, v72
	v_exp_f32_e32 v73, v73
	v_exp_f32_e32 v74, v74
	v_exp_f32_e32 v75, v75
	v_exp_f32_e32 v76, v76
	v_exp_f32_e32 v77, v77
	v_add_f32_e32 v70, 1.0, v70
	v_add_f32_e32 v71, 1.0, v71
	v_add_f32_e32 v72, 1.0, v72
	v_add_f32_e32 v73, 1.0, v73
	v_add_f32_e32 v74, 1.0, v74
	v_add_f32_e32 v75, 1.0, v75
	v_add_f32_e32 v76, 1.0, v76
	v_add_f32_e32 v77, 1.0, v77
	v_rcp_f32_e32 v70, v70
	v_rcp_f32_e32 v71, v71
	v_rcp_f32_e32 v72, v72
	v_rcp_f32_e32 v73, v73
	v_rcp_f32_e32 v74, v74
	v_rcp_f32_e32 v75, v75
	v_rcp_f32_e32 v76, v76
	v_rcp_f32_e32 v77, v77
	v_mul_f32_e32 v60, v60, v70
	v_mul_f32_e32 v61, v61, v71
	v_mul_f32_e32 v62, v62, v72
	v_mul_f32_e32 v63, v63, v73
	v_mul_f32_e32 v64, v64, v74
	v_mul_f32_e32 v65, v65, v75
	v_mul_f32_e32 v66, v66, v76
	v_mul_f32_e32 v67, v67, v77
	ds_write_b32 v3, v60
	ds_write_b32 v3, v61 offset:2048
	ds_write_b32 v3, v62 offset:4096
	ds_write_b32 v3, v63 offset:6144
	ds_write_b32 v3, v64 offset:8192
	ds_write_b32 v3, v65 offset:10240
	ds_write_b32 v3, v66 offset:12288
	ds_write_b32 v3, v67 offset:14336
.LBB0_16:
	s_or_b64 exec, exec, s[0:1]
	s_waitcnt lgkmcnt(0)
	s_barrier
	s_load_dwordx2 s[4:5], s[8:9], 0x10
	v_ashrrev_i32_e32 v3, 31, v2
	v_lshlrev_b32_e32 v4, 2, v54
	v_mov_b32_e32 v5, 0
	s_lshl_b32 s0, s3, 7
	v_mov_b32_e32 v1, 0x9000
	s_waitcnt lgkmcnt(0)
	v_lshl_add_u64 v[6:7], v[2:3], 2, s[4:5]
	v_lshl_add_u64 v[6:7], v[6:7], 0, v[4:5]
	v_add_u32_e32 v8, s10, v4
	v_mad_u64_u32 v[6:7], s[6:7], s0, v1, v[6:7]
	ds_read2st64_b32 v[14:15], v8 offset1:1
	ds_read2st64_b32 v[12:13], v8 offset0:16 offset1:17
	ds_read2st64_b32 v[10:11], v8 offset0:32 offset1:33
	ds_read2st64_b32 v[8:9], v8 offset0:48 offset1:49
	s_mov_b64 s[12:13], 0x9000
	s_lshl_b32 s1, s3, 10
	s_add_i32 s1, s1, 0
	s_mov_b32 s4, 0x9000
	global_load_dword v64, v[6:7], off
	v_lshl_add_u64 v[6:7], v[6:7], 0, s[12:13]
	global_load_dword v65, v[6:7], off
	v_lshl_add_u64 v[6:7], v[6:7], 0, s[12:13]
	global_load_dword v66, v[6:7], off
	v_lshl_add_u64 v[6:7], v[6:7], 0, s[12:13]
	global_load_dword v67, v[6:7], off
	v_lshl_add_u64 v[6:7], v[6:7], 0, s[12:13]
	global_load_dword v68, v[6:7], off
	v_lshl_add_u64 v[6:7], v[6:7], 0, s[12:13]
	global_load_dword v69, v[6:7], off
	v_lshl_add_u64 v[6:7], v[6:7], 0, s[12:13]
	global_load_dword v70, v[6:7], off
	v_lshl_add_u64 v[6:7], v[6:7], 0, s[12:13]
	global_load_dword v71, v[6:7], off
	v_lshl_add_u64 v[6:7], v[6:7], 0, s[12:13]
	global_load_dword v72, v[6:7], off
	v_lshl_add_u64 v[6:7], v[6:7], 0, s[12:13]
	global_load_dword v73, v[6:7], off
	v_lshl_add_u64 v[6:7], v[6:7], 0, s[12:13]
	global_load_dword v74, v[6:7], off
	v_lshl_add_u64 v[6:7], v[6:7], 0, s[12:13]
	global_load_dword v75, v[6:7], off
	v_lshl_add_u64 v[6:7], v[6:7], 0, s[12:13]
	global_load_dword v76, v[6:7], off
	v_lshl_add_u64 v[6:7], v[6:7], 0, s[12:13]
	global_load_dword v77, v[6:7], off
	v_lshl_add_u64 v[6:7], v[6:7], 0, s[12:13]
	global_load_dword v78, v[6:7], off
	v_lshl_add_u64 v[6:7], v[6:7], 0, s[12:13]
	global_load_dword v79, v[6:7], off
	v_lshl_add_u64 v[6:7], v[6:7], 0, s[12:13]
	global_load_dword v80, v[6:7], off
	v_lshl_add_u64 v[6:7], v[6:7], 0, s[12:13]
	global_load_dword v81, v[6:7], off
	v_lshl_add_u64 v[6:7], v[6:7], 0, s[12:13]
	global_load_dword v82, v[6:7], off
	v_lshl_add_u64 v[6:7], v[6:7], 0, s[12:13]
	global_load_dword v83, v[6:7], off
	v_lshl_add_u64 v[6:7], v[6:7], 0, s[12:13]
	global_load_dword v84, v[6:7], off
	v_lshl_add_u64 v[6:7], v[6:7], 0, s[12:13]
	global_load_dword v85, v[6:7], off
	v_lshl_add_u64 v[6:7], v[6:7], 0, s[12:13]
	global_load_dword v86, v[6:7], off
	v_lshl_add_u64 v[6:7], v[6:7], 0, s[12:13]
	global_load_dword v87, v[6:7], off
	v_lshl_add_u64 v[6:7], v[6:7], 0, s[12:13]
	global_load_dword v88, v[6:7], off
	v_lshl_add_u64 v[6:7], v[6:7], 0, s[12:13]
	global_load_dword v89, v[6:7], off
	v_lshl_add_u64 v[6:7], v[6:7], 0, s[12:13]
	global_load_dword v90, v[6:7], off
	v_lshl_add_u64 v[6:7], v[6:7], 0, s[12:13]
	global_load_dword v91, v[6:7], off
	v_lshl_add_u64 v[6:7], v[6:7], 0, s[12:13]
	global_load_dword v92, v[6:7], off
	v_lshl_add_u64 v[6:7], v[6:7], 0, s[12:13]
	global_load_dword v93, v[6:7], off
	v_lshl_add_u64 v[6:7], v[6:7], 0, s[12:13]
	global_load_dword v94, v[6:7], off
	v_lshl_add_u64 v[6:7], v[6:7], 0, s[12:13]
	global_load_dword v95, v[6:7], off
	v_lshl_add_u64 v[6:7], v[6:7], 0, s[12:13]
	global_load_dword v96, v[6:7], off
	v_lshl_add_u64 v[6:7], v[6:7], 0, s[12:13]
	global_load_dword v97, v[6:7], off
	v_lshl_add_u64 v[6:7], v[6:7], 0, s[12:13]
	global_load_dword v98, v[6:7], off
	v_lshl_add_u64 v[6:7], v[6:7], 0, s[12:13]
	global_load_dword v99, v[6:7], off
	v_lshl_add_u64 v[6:7], v[6:7], 0, s[12:13]
	global_load_dword v100, v[6:7], off
	v_lshl_add_u64 v[6:7], v[6:7], 0, s[12:13]
	global_load_dword v101, v[6:7], off
	v_lshl_add_u64 v[6:7], v[6:7], 0, s[12:13]
	global_load_dword v102, v[6:7], off
	v_lshl_add_u64 v[6:7], v[6:7], 0, s[12:13]
	global_load_dword v103, v[6:7], off
	v_lshl_add_u64 v[6:7], v[6:7], 0, s[12:13]
	global_load_dword v104, v[6:7], off
	v_lshl_add_u64 v[6:7], v[6:7], 0, s[12:13]
	global_load_dword v105, v[6:7], off
	v_lshl_add_u64 v[6:7], v[6:7], 0, s[12:13]
	global_load_dword v106, v[6:7], off
	v_lshl_add_u64 v[6:7], v[6:7], 0, s[12:13]
	global_load_dword v107, v[6:7], off
	v_lshl_add_u64 v[6:7], v[6:7], 0, s[12:13]
	global_load_dword v108, v[6:7], off
	v_lshl_add_u64 v[6:7], v[6:7], 0, s[12:13]
	global_load_dword v109, v[6:7], off
	v_lshl_add_u64 v[6:7], v[6:7], 0, s[12:13]
	global_load_dword v110, v[6:7], off
	v_lshl_add_u64 v[6:7], v[6:7], 0, s[12:13]
	global_load_dword v111, v[6:7], off
	v_lshl_add_u64 v[6:7], v[6:7], 0, s[12:13]
	global_load_dword v112, v[6:7], off
	v_lshl_add_u64 v[6:7], v[6:7], 0, s[12:13]
	global_load_dword v113, v[6:7], off
	v_lshl_add_u64 v[6:7], v[6:7], 0, s[12:13]
	global_load_dword v114, v[6:7], off
	v_lshl_add_u64 v[6:7], v[6:7], 0, s[12:13]
	global_load_dword v115, v[6:7], off
	v_lshl_add_u64 v[6:7], v[6:7], 0, s[12:13]
	global_load_dword v116, v[6:7], off
	v_lshl_add_u64 v[6:7], v[6:7], 0, s[12:13]
	global_load_dword v117, v[6:7], off
	v_lshl_add_u64 v[6:7], v[6:7], 0, s[12:13]
	global_load_dword v118, v[6:7], off
	v_lshl_add_u64 v[6:7], v[6:7], 0, s[12:13]
	global_load_dword v119, v[6:7], off
	v_lshl_add_u64 v[6:7], v[6:7], 0, s[12:13]
	s_waitcnt lgkmcnt(0)
	s_waitcnt vmcnt(55)
	v_readlane_b32 s20, v14, 0
	v_readlane_b32 s21, v12, 0
	v_readlane_b32 s22, v10, 0
	v_readlane_b32 s23, v8, 0
	v_fma_f32 v16, v64, s20, 0
	v_fma_f32 v17, v64, s21, 0
	v_fma_f32 v18, v64, s22, 0
	v_fma_f32 v19, v64, s23, 0
	global_load_dword v64, v[6:7], off
	v_lshl_add_u64 v[6:7], v[6:7], 0, s[12:13]
	s_waitcnt vmcnt(55)
	v_readlane_b32 s20, v14, 1
	v_readlane_b32 s21, v12, 1
	v_readlane_b32 s22, v10, 1
	v_readlane_b32 s23, v8, 1
	v_fmac_f32_e32 v16, s20, v65
	v_fmac_f32_e32 v17, s21, v65
	v_fmac_f32_e32 v18, s22, v65
	v_fmac_f32_e32 v19, s23, v65
	global_load_dword v65, v[6:7], off
	v_lshl_add_u64 v[6:7], v[6:7], 0, s[12:13]
	s_waitcnt vmcnt(55)
	v_readlane_b32 s20, v14, 2
	v_readlane_b32 s21, v12, 2
	v_readlane_b32 s22, v10, 2
	v_readlane_b32 s23, v8, 2
	v_fmac_f32_e32 v16, s20, v66
	v_fmac_f32_e32 v17, s21, v66
	v_fmac_f32_e32 v18, s22, v66
	v_fmac_f32_e32 v19, s23, v66
	global_load_dword v66, v[6:7], off
	v_lshl_add_u64 v[6:7], v[6:7], 0, s[12:13]
	s_waitcnt vmcnt(55)
	v_readlane_b32 s20, v14, 3
	v_readlane_b32 s21, v12, 3
	v_readlane_b32 s22, v10, 3
	v_readlane_b32 s23, v8, 3
	v_fmac_f32_e32 v16, s20, v67
	v_fmac_f32_e32 v17, s21, v67
	v_fmac_f32_e32 v18, s22, v67
	v_fmac_f32_e32 v19, s23, v67
	global_load_dword v67, v[6:7], off
	v_lshl_add_u64 v[6:7], v[6:7], 0, s[12:13]
	s_waitcnt vmcnt(55)
	v_readlane_b32 s20, v14, 4
	v_readlane_b32 s21, v12, 4
	v_readlane_b32 s22, v10, 4
	v_readlane_b32 s23, v8, 4
	v_fmac_f32_e32 v16, s20, v68
	v_fmac_f32_e32 v17, s21, v68
	v_fmac_f32_e32 v18, s22, v68
	v_fmac_f32_e32 v19, s23, v68
	global_load_dword v68, v[6:7], off
	v_lshl_add_u64 v[6:7], v[6:7], 0, s[12:13]
	s_waitcnt vmcnt(55)
	v_readlane_b32 s20, v14, 5
	v_readlane_b32 s21, v12, 5
	v_readlane_b32 s22, v10, 5
	v_readlane_b32 s23, v8, 5
	v_fmac_f32_e32 v16, s20, v69
	v_fmac_f32_e32 v17, s21, v69
	v_fmac_f32_e32 v18, s22, v69
	v_fmac_f32_e32 v19, s23, v69
	global_load_dword v69, v[6:7], off
	v_lshl_add_u64 v[6:7], v[6:7], 0, s[12:13]
	s_waitcnt vmcnt(55)
	v_readlane_b32 s20, v14, 6
	v_readlane_b32 s21, v12, 6
	v_readlane_b32 s22, v10, 6
	v_readlane_b32 s23, v8, 6
	v_fmac_f32_e32 v16, s20, v70
	v_fmac_f32_e32 v17, s21, v70
	v_fmac_f32_e32 v18, s22, v70
	v_fmac_f32_e32 v19, s23, v70
	global_load_dword v70, v[6:7], off
	v_lshl_add_u64 v[6:7], v[6:7], 0, s[12:13]
	s_waitcnt vmcnt(55)
	v_readlane_b32 s20, v14, 7
	v_readlane_b32 s21, v12, 7
	v_readlane_b32 s22, v10, 7
	v_readlane_b32 s23, v8, 7
	v_fmac_f32_e32 v16, s20, v71
	v_fmac_f32_e32 v17, s21, v71
	v_fmac_f32_e32 v18, s22, v71
	v_fmac_f32_e32 v19, s23, v71
	global_load_dword v71, v[6:7], off
	v_lshl_add_u64 v[6:7], v[6:7], 0, s[12:13]
	s_waitcnt vmcnt(55)
	v_readlane_b32 s20, v14, 8
	v_readlane_b32 s21, v12, 8
	v_readlane_b32 s22, v10, 8
	v_readlane_b32 s23, v8, 8
	v_fmac_f32_e32 v16, s20, v72
	v_fmac_f32_e32 v17, s21, v72
	v_fmac_f32_e32 v18, s22, v72
	v_fmac_f32_e32 v19, s23, v72
	global_load_dword v72, v[6:7], off
	v_lshl_add_u64 v[6:7], v[6:7], 0, s[12:13]
	s_waitcnt vmcnt(55)
	v_readlane_b32 s20, v14, 9
	v_readlane_b32 s21, v12, 9
	v_readlane_b32 s22, v10, 9
	v_readlane_b32 s23, v8, 9
	v_fmac_f32_e32 v16, s20, v73
	v_fmac_f32_e32 v17, s21, v73
	v_fmac_f32_e32 v18, s22, v73
	v_fmac_f32_e32 v19, s23, v73
	global_load_dword v73, v[6:7], off
	v_lshl_add_u64 v[6:7], v[6:7], 0, s[12:13]
	s_waitcnt vmcnt(55)
	v_readlane_b32 s20, v14, 10
	v_readlane_b32 s21, v12, 10
	v_readlane_b32 s22, v10, 10
	v_readlane_b32 s23, v8, 10
	v_fmac_f32_e32 v16, s20, v74
	v_fmac_f32_e32 v17, s21, v74
	v_fmac_f32_e32 v18, s22, v74
	v_fmac_f32_e32 v19, s23, v74
	global_load_dword v74, v[6:7], off
	v_lshl_add_u64 v[6:7], v[6:7], 0, s[12:13]
	s_waitcnt vmcnt(55)
	v_readlane_b32 s20, v14, 11
	v_readlane_b32 s21, v12, 11
	v_readlane_b32 s22, v10, 11
	v_readlane_b32 s23, v8, 11
	v_fmac_f32_e32 v16, s20, v75
	v_fmac_f32_e32 v17, s21, v75
	v_fmac_f32_e32 v18, s22, v75
	v_fmac_f32_e32 v19, s23, v75
	global_load_dword v75, v[6:7], off
	v_lshl_add_u64 v[6:7], v[6:7], 0, s[12:13]
	s_waitcnt vmcnt(55)
	v_readlane_b32 s20, v14, 12
	v_readlane_b32 s21, v12, 12
	v_readlane_b32 s22, v10, 12
	v_readlane_b32 s23, v8, 12
	v_fmac_f32_e32 v16, s20, v76
	v_fmac_f32_e32 v17, s21, v76
	v_fmac_f32_e32 v18, s22, v76
	v_fmac_f32_e32 v19, s23, v76
	global_load_dword v76, v[6:7], off
	v_lshl_add_u64 v[6:7], v[6:7], 0, s[12:13]
	s_waitcnt vmcnt(55)
	v_readlane_b32 s20, v14, 13
	v_readlane_b32 s21, v12, 13
	v_readlane_b32 s22, v10, 13
	v_readlane_b32 s23, v8, 13
	v_fmac_f32_e32 v16, s20, v77
	v_fmac_f32_e32 v17, s21, v77
	v_fmac_f32_e32 v18, s22, v77
	v_fmac_f32_e32 v19, s23, v77
	global_load_dword v77, v[6:7], off
	v_lshl_add_u64 v[6:7], v[6:7], 0, s[12:13]
	s_waitcnt vmcnt(55)
	v_readlane_b32 s20, v14, 14
	v_readlane_b32 s21, v12, 14
	v_readlane_b32 s22, v10, 14
	v_readlane_b32 s23, v8, 14
	v_fmac_f32_e32 v16, s20, v78
	v_fmac_f32_e32 v17, s21, v78
	v_fmac_f32_e32 v18, s22, v78
	v_fmac_f32_e32 v19, s23, v78
	global_load_dword v78, v[6:7], off
	v_lshl_add_u64 v[6:7], v[6:7], 0, s[12:13]
	s_waitcnt vmcnt(55)
	v_readlane_b32 s20, v14, 15
	v_readlane_b32 s21, v12, 15
	v_readlane_b32 s22, v10, 15
	v_readlane_b32 s23, v8, 15
	v_fmac_f32_e32 v16, s20, v79
	v_fmac_f32_e32 v17, s21, v79
	v_fmac_f32_e32 v18, s22, v79
	v_fmac_f32_e32 v19, s23, v79
	global_load_dword v79, v[6:7], off
	v_lshl_add_u64 v[6:7], v[6:7], 0, s[12:13]
	s_waitcnt vmcnt(55)
	v_readlane_b32 s20, v14, 16
	v_readlane_b32 s21, v12, 16
	v_readlane_b32 s22, v10, 16
	v_readlane_b32 s23, v8, 16
	v_fmac_f32_e32 v16, s20, v80
	v_fmac_f32_e32 v17, s21, v80
	v_fmac_f32_e32 v18, s22, v80
	v_fmac_f32_e32 v19, s23, v80
	global_load_dword v80, v[6:7], off
	v_lshl_add_u64 v[6:7], v[6:7], 0, s[12:13]
	s_waitcnt vmcnt(55)
	v_readlane_b32 s20, v14, 17
	v_readlane_b32 s21, v12, 17
	v_readlane_b32 s22, v10, 17
	v_readlane_b32 s23, v8, 17
	v_fmac_f32_e32 v16, s20, v81
	v_fmac_f32_e32 v17, s21, v81
	v_fmac_f32_e32 v18, s22, v81
	v_fmac_f32_e32 v19, s23, v81
	global_load_dword v81, v[6:7], off
	v_lshl_add_u64 v[6:7], v[6:7], 0, s[12:13]
	s_waitcnt vmcnt(55)
	v_readlane_b32 s20, v14, 18
	v_readlane_b32 s21, v12, 18
	v_readlane_b32 s22, v10, 18
	v_readlane_b32 s23, v8, 18
	v_fmac_f32_e32 v16, s20, v82
	v_fmac_f32_e32 v17, s21, v82
	v_fmac_f32_e32 v18, s22, v82
	v_fmac_f32_e32 v19, s23, v82
	global_load_dword v82, v[6:7], off
	v_lshl_add_u64 v[6:7], v[6:7], 0, s[12:13]
	s_waitcnt vmcnt(55)
	v_readlane_b32 s20, v14, 19
	v_readlane_b32 s21, v12, 19
	v_readlane_b32 s22, v10, 19
	v_readlane_b32 s23, v8, 19
	v_fmac_f32_e32 v16, s20, v83
	v_fmac_f32_e32 v17, s21, v83
	v_fmac_f32_e32 v18, s22, v83
	v_fmac_f32_e32 v19, s23, v83
	global_load_dword v83, v[6:7], off
	v_lshl_add_u64 v[6:7], v[6:7], 0, s[12:13]
	s_waitcnt vmcnt(55)
	v_readlane_b32 s20, v14, 20
	v_readlane_b32 s21, v12, 20
	v_readlane_b32 s22, v10, 20
	v_readlane_b32 s23, v8, 20
	v_fmac_f32_e32 v16, s20, v84
	v_fmac_f32_e32 v17, s21, v84
	v_fmac_f32_e32 v18, s22, v84
	v_fmac_f32_e32 v19, s23, v84
	global_load_dword v84, v[6:7], off
	v_lshl_add_u64 v[6:7], v[6:7], 0, s[12:13]
	s_waitcnt vmcnt(55)
	v_readlane_b32 s20, v14, 21
	v_readlane_b32 s21, v12, 21
	v_readlane_b32 s22, v10, 21
	v_readlane_b32 s23, v8, 21
	v_fmac_f32_e32 v16, s20, v85
	v_fmac_f32_e32 v17, s21, v85
	v_fmac_f32_e32 v18, s22, v85
	v_fmac_f32_e32 v19, s23, v85
	global_load_dword v85, v[6:7], off
	v_lshl_add_u64 v[6:7], v[6:7], 0, s[12:13]
	s_waitcnt vmcnt(55)
	v_readlane_b32 s20, v14, 22
	v_readlane_b32 s21, v12, 22
	v_readlane_b32 s22, v10, 22
	v_readlane_b32 s23, v8, 22
	v_fmac_f32_e32 v16, s20, v86
	v_fmac_f32_e32 v17, s21, v86
	v_fmac_f32_e32 v18, s22, v86
	v_fmac_f32_e32 v19, s23, v86
	global_load_dword v86, v[6:7], off
	v_lshl_add_u64 v[6:7], v[6:7], 0, s[12:13]
	s_waitcnt vmcnt(55)
	v_readlane_b32 s20, v14, 23
	v_readlane_b32 s21, v12, 23
	v_readlane_b32 s22, v10, 23
	v_readlane_b32 s23, v8, 23
	v_fmac_f32_e32 v16, s20, v87
	v_fmac_f32_e32 v17, s21, v87
	v_fmac_f32_e32 v18, s22, v87
	v_fmac_f32_e32 v19, s23, v87
	global_load_dword v87, v[6:7], off
	v_lshl_add_u64 v[6:7], v[6:7], 0, s[12:13]
	s_waitcnt vmcnt(55)
	v_readlane_b32 s20, v14, 24
	v_readlane_b32 s21, v12, 24
	v_readlane_b32 s22, v10, 24
	v_readlane_b32 s23, v8, 24
	v_fmac_f32_e32 v16, s20, v88
	v_fmac_f32_e32 v17, s21, v88
	v_fmac_f32_e32 v18, s22, v88
	v_fmac_f32_e32 v19, s23, v88
	global_load_dword v88, v[6:7], off
	v_lshl_add_u64 v[6:7], v[6:7], 0, s[12:13]
	s_waitcnt vmcnt(55)
	v_readlane_b32 s20, v14, 25
	v_readlane_b32 s21, v12, 25
	v_readlane_b32 s22, v10, 25
	v_readlane_b32 s23, v8, 25
	v_fmac_f32_e32 v16, s20, v89
	v_fmac_f32_e32 v17, s21, v89
	v_fmac_f32_e32 v18, s22, v89
	v_fmac_f32_e32 v19, s23, v89
	global_load_dword v89, v[6:7], off
	v_lshl_add_u64 v[6:7], v[6:7], 0, s[12:13]
	s_waitcnt vmcnt(55)
	v_readlane_b32 s20, v14, 26
	v_readlane_b32 s21, v12, 26
	v_readlane_b32 s22, v10, 26
	v_readlane_b32 s23, v8, 26
	v_fmac_f32_e32 v16, s20, v90
	v_fmac_f32_e32 v17, s21, v90
	v_fmac_f32_e32 v18, s22, v90
	v_fmac_f32_e32 v19, s23, v90
	global_load_dword v90, v[6:7], off
	v_lshl_add_u64 v[6:7], v[6:7], 0, s[12:13]
	s_waitcnt vmcnt(55)
	v_readlane_b32 s20, v14, 27
	v_readlane_b32 s21, v12, 27
	v_readlane_b32 s22, v10, 27
	v_readlane_b32 s23, v8, 27
	v_fmac_f32_e32 v16, s20, v91
	v_fmac_f32_e32 v17, s21, v91
	v_fmac_f32_e32 v18, s22, v91
	v_fmac_f32_e32 v19, s23, v91
	global_load_dword v91, v[6:7], off
	v_lshl_add_u64 v[6:7], v[6:7], 0, s[12:13]
	s_waitcnt vmcnt(55)
	v_readlane_b32 s20, v14, 28
	v_readlane_b32 s21, v12, 28
	v_readlane_b32 s22, v10, 28
	v_readlane_b32 s23, v8, 28
	v_fmac_f32_e32 v16, s20, v92
	v_fmac_f32_e32 v17, s21, v92
	v_fmac_f32_e32 v18, s22, v92
	v_fmac_f32_e32 v19, s23, v92
	global_load_dword v92, v[6:7], off
	v_lshl_add_u64 v[6:7], v[6:7], 0, s[12:13]
	s_waitcnt vmcnt(55)
	v_readlane_b32 s20, v14, 29
	v_readlane_b32 s21, v12, 29
	v_readlane_b32 s22, v10, 29
	v_readlane_b32 s23, v8, 29
	v_fmac_f32_e32 v16, s20, v93
	v_fmac_f32_e32 v17, s21, v93
	v_fmac_f32_e32 v18, s22, v93
	v_fmac_f32_e32 v19, s23, v93
	global_load_dword v93, v[6:7], off
	v_lshl_add_u64 v[6:7], v[6:7], 0, s[12:13]
	s_waitcnt vmcnt(55)
	v_readlane_b32 s20, v14, 30
	v_readlane_b32 s21, v12, 30
	v_readlane_b32 s22, v10, 30
	v_readlane_b32 s23, v8, 30
	v_fmac_f32_e32 v16, s20, v94
	v_fmac_f32_e32 v17, s21, v94
	v_fmac_f32_e32 v18, s22, v94
	v_fmac_f32_e32 v19, s23, v94
	global_load_dword v94, v[6:7], off
	v_lshl_add_u64 v[6:7], v[6:7], 0, s[12:13]
	s_waitcnt vmcnt(55)
	v_readlane_b32 s20, v14, 31
	v_readlane_b32 s21, v12, 31
	v_readlane_b32 s22, v10, 31
	v_readlane_b32 s23, v8, 31
	v_fmac_f32_e32 v16, s20, v95
	v_fmac_f32_e32 v17, s21, v95
	v_fmac_f32_e32 v18, s22, v95
	v_fmac_f32_e32 v19, s23, v95
	global_load_dword v95, v[6:7], off
	v_lshl_add_u64 v[6:7], v[6:7], 0, s[12:13]
	s_waitcnt vmcnt(55)
	v_readlane_b32 s20, v14, 32
	v_readlane_b32 s21, v12, 32
	v_readlane_b32 s22, v10, 32
	v_readlane_b32 s23, v8, 32
	v_fmac_f32_e32 v16, s20, v96
	v_fmac_f32_e32 v17, s21, v96
	v_fmac_f32_e32 v18, s22, v96
	v_fmac_f32_e32 v19, s23, v96
	global_load_dword v96, v[6:7], off
	v_lshl_add_u64 v[6:7], v[6:7], 0, s[12:13]
	s_waitcnt vmcnt(55)
	v_readlane_b32 s20, v14, 33
	v_readlane_b32 s21, v12, 33
	v_readlane_b32 s22, v10, 33
	v_readlane_b32 s23, v8, 33
	v_fmac_f32_e32 v16, s20, v97
	v_fmac_f32_e32 v17, s21, v97
	v_fmac_f32_e32 v18, s22, v97
	v_fmac_f32_e32 v19, s23, v97
	global_load_dword v97, v[6:7], off
	v_lshl_add_u64 v[6:7], v[6:7], 0, s[12:13]
	s_waitcnt vmcnt(55)
	v_readlane_b32 s20, v14, 34
	v_readlane_b32 s21, v12, 34
	v_readlane_b32 s22, v10, 34
	v_readlane_b32 s23, v8, 34
	v_fmac_f32_e32 v16, s20, v98
	v_fmac_f32_e32 v17, s21, v98
	v_fmac_f32_e32 v18, s22, v98
	v_fmac_f32_e32 v19, s23, v98
	global_load_dword v98, v[6:7], off
	v_lshl_add_u64 v[6:7], v[6:7], 0, s[12:13]
	s_waitcnt vmcnt(55)
	v_readlane_b32 s20, v14, 35
	v_readlane_b32 s21, v12, 35
	v_readlane_b32 s22, v10, 35
	v_readlane_b32 s23, v8, 35
	v_fmac_f32_e32 v16, s20, v99
	v_fmac_f32_e32 v17, s21, v99
	v_fmac_f32_e32 v18, s22, v99
	v_fmac_f32_e32 v19, s23, v99
	global_load_dword v99, v[6:7], off
	v_lshl_add_u64 v[6:7], v[6:7], 0, s[12:13]
	s_waitcnt vmcnt(55)
	v_readlane_b32 s20, v14, 36
	v_readlane_b32 s21, v12, 36
	v_readlane_b32 s22, v10, 36
	v_readlane_b32 s23, v8, 36
	v_fmac_f32_e32 v16, s20, v100
	v_fmac_f32_e32 v17, s21, v100
	v_fmac_f32_e32 v18, s22, v100
	v_fmac_f32_e32 v19, s23, v100
	global_load_dword v100, v[6:7], off
	v_lshl_add_u64 v[6:7], v[6:7], 0, s[12:13]
	s_waitcnt vmcnt(55)
	v_readlane_b32 s20, v14, 37
	v_readlane_b32 s21, v12, 37
	v_readlane_b32 s22, v10, 37
	v_readlane_b32 s23, v8, 37
	v_fmac_f32_e32 v16, s20, v101
	v_fmac_f32_e32 v17, s21, v101
	v_fmac_f32_e32 v18, s22, v101
	v_fmac_f32_e32 v19, s23, v101
	global_load_dword v101, v[6:7], off
	v_lshl_add_u64 v[6:7], v[6:7], 0, s[12:13]
	s_waitcnt vmcnt(55)
	v_readlane_b32 s20, v14, 38
	v_readlane_b32 s21, v12, 38
	v_readlane_b32 s22, v10, 38
	v_readlane_b32 s23, v8, 38
	v_fmac_f32_e32 v16, s20, v102
	v_fmac_f32_e32 v17, s21, v102
	v_fmac_f32_e32 v18, s22, v102
	v_fmac_f32_e32 v19, s23, v102
	global_load_dword v102, v[6:7], off
	v_lshl_add_u64 v[6:7], v[6:7], 0, s[12:13]
	s_waitcnt vmcnt(55)
	v_readlane_b32 s20, v14, 39
	v_readlane_b32 s21, v12, 39
	v_readlane_b32 s22, v10, 39
	v_readlane_b32 s23, v8, 39
	v_fmac_f32_e32 v16, s20, v103
	v_fmac_f32_e32 v17, s21, v103
	v_fmac_f32_e32 v18, s22, v103
	v_fmac_f32_e32 v19, s23, v103
	global_load_dword v103, v[6:7], off
	v_lshl_add_u64 v[6:7], v[6:7], 0, s[12:13]
	s_waitcnt vmcnt(55)
	v_readlane_b32 s20, v14, 40
	v_readlane_b32 s21, v12, 40
	v_readlane_b32 s22, v10, 40
	v_readlane_b32 s23, v8, 40
	v_fmac_f32_e32 v16, s20, v104
	v_fmac_f32_e32 v17, s21, v104
	v_fmac_f32_e32 v18, s22, v104
	v_fmac_f32_e32 v19, s23, v104
	global_load_dword v104, v[6:7], off
	v_lshl_add_u64 v[6:7], v[6:7], 0, s[12:13]
	s_waitcnt vmcnt(55)
	v_readlane_b32 s20, v14, 41
	v_readlane_b32 s21, v12, 41
	v_readlane_b32 s22, v10, 41
	v_readlane_b32 s23, v8, 41
	v_fmac_f32_e32 v16, s20, v105
	v_fmac_f32_e32 v17, s21, v105
	v_fmac_f32_e32 v18, s22, v105
	v_fmac_f32_e32 v19, s23, v105
	global_load_dword v105, v[6:7], off
	v_lshl_add_u64 v[6:7], v[6:7], 0, s[12:13]
	s_waitcnt vmcnt(55)
	v_readlane_b32 s20, v14, 42
	v_readlane_b32 s21, v12, 42
	v_readlane_b32 s22, v10, 42
	v_readlane_b32 s23, v8, 42
	v_fmac_f32_e32 v16, s20, v106
	v_fmac_f32_e32 v17, s21, v106
	v_fmac_f32_e32 v18, s22, v106
	v_fmac_f32_e32 v19, s23, v106
	global_load_dword v106, v[6:7], off
	v_lshl_add_u64 v[6:7], v[6:7], 0, s[12:13]
	s_waitcnt vmcnt(55)
	v_readlane_b32 s20, v14, 43
	v_readlane_b32 s21, v12, 43
	v_readlane_b32 s22, v10, 43
	v_readlane_b32 s23, v8, 43
	v_fmac_f32_e32 v16, s20, v107
	v_fmac_f32_e32 v17, s21, v107
	v_fmac_f32_e32 v18, s22, v107
	v_fmac_f32_e32 v19, s23, v107
	global_load_dword v107, v[6:7], off
	v_lshl_add_u64 v[6:7], v[6:7], 0, s[12:13]
	s_waitcnt vmcnt(55)
	v_readlane_b32 s20, v14, 44
	v_readlane_b32 s21, v12, 44
	v_readlane_b32 s22, v10, 44
	v_readlane_b32 s23, v8, 44
	v_fmac_f32_e32 v16, s20, v108
	v_fmac_f32_e32 v17, s21, v108
	v_fmac_f32_e32 v18, s22, v108
	v_fmac_f32_e32 v19, s23, v108
	global_load_dword v108, v[6:7], off
	v_lshl_add_u64 v[6:7], v[6:7], 0, s[12:13]
	s_waitcnt vmcnt(55)
	v_readlane_b32 s20, v14, 45
	v_readlane_b32 s21, v12, 45
	v_readlane_b32 s22, v10, 45
	v_readlane_b32 s23, v8, 45
	v_fmac_f32_e32 v16, s20, v109
	v_fmac_f32_e32 v17, s21, v109
	v_fmac_f32_e32 v18, s22, v109
	v_fmac_f32_e32 v19, s23, v109
	global_load_dword v109, v[6:7], off
	v_lshl_add_u64 v[6:7], v[6:7], 0, s[12:13]
	s_waitcnt vmcnt(55)
	v_readlane_b32 s20, v14, 46
	v_readlane_b32 s21, v12, 46
	v_readlane_b32 s22, v10, 46
	v_readlane_b32 s23, v8, 46
	v_fmac_f32_e32 v16, s20, v110
	v_fmac_f32_e32 v17, s21, v110
	v_fmac_f32_e32 v18, s22, v110
	v_fmac_f32_e32 v19, s23, v110
	global_load_dword v110, v[6:7], off
	v_lshl_add_u64 v[6:7], v[6:7], 0, s[12:13]
	s_waitcnt vmcnt(55)
	v_readlane_b32 s20, v14, 47
	v_readlane_b32 s21, v12, 47
	v_readlane_b32 s22, v10, 47
	v_readlane_b32 s23, v8, 47
	v_fmac_f32_e32 v16, s20, v111
	v_fmac_f32_e32 v17, s21, v111
	v_fmac_f32_e32 v18, s22, v111
	v_fmac_f32_e32 v19, s23, v111
	global_load_dword v111, v[6:7], off
	v_lshl_add_u64 v[6:7], v[6:7], 0, s[12:13]
	s_waitcnt vmcnt(55)
	v_readlane_b32 s20, v14, 48
	v_readlane_b32 s21, v12, 48
	v_readlane_b32 s22, v10, 48
	v_readlane_b32 s23, v8, 48
	v_fmac_f32_e32 v16, s20, v112
	v_fmac_f32_e32 v17, s21, v112
	v_fmac_f32_e32 v18, s22, v112
	v_fmac_f32_e32 v19, s23, v112
	global_load_dword v112, v[6:7], off
	v_lshl_add_u64 v[6:7], v[6:7], 0, s[12:13]
	s_waitcnt vmcnt(55)
	v_readlane_b32 s20, v14, 49
	v_readlane_b32 s21, v12, 49
	v_readlane_b32 s22, v10, 49
	v_readlane_b32 s23, v8, 49
	v_fmac_f32_e32 v16, s20, v113
	v_fmac_f32_e32 v17, s21, v113
	v_fmac_f32_e32 v18, s22, v113
	v_fmac_f32_e32 v19, s23, v113
	global_load_dword v113, v[6:7], off
	v_lshl_add_u64 v[6:7], v[6:7], 0, s[12:13]
	s_waitcnt vmcnt(55)
	v_readlane_b32 s20, v14, 50
	v_readlane_b32 s21, v12, 50
	v_readlane_b32 s22, v10, 50
	v_readlane_b32 s23, v8, 50
	v_fmac_f32_e32 v16, s20, v114
	v_fmac_f32_e32 v17, s21, v114
	v_fmac_f32_e32 v18, s22, v114
	v_fmac_f32_e32 v19, s23, v114
	global_load_dword v114, v[6:7], off
	v_lshl_add_u64 v[6:7], v[6:7], 0, s[12:13]
	s_waitcnt vmcnt(55)
	v_readlane_b32 s20, v14, 51
	v_readlane_b32 s21, v12, 51
	v_readlane_b32 s22, v10, 51
	v_readlane_b32 s23, v8, 51
	v_fmac_f32_e32 v16, s20, v115
	v_fmac_f32_e32 v17, s21, v115
	v_fmac_f32_e32 v18, s22, v115
	v_fmac_f32_e32 v19, s23, v115
	global_load_dword v115, v[6:7], off
	v_lshl_add_u64 v[6:7], v[6:7], 0, s[12:13]
	s_waitcnt vmcnt(55)
	v_readlane_b32 s20, v14, 52
	v_readlane_b32 s21, v12, 52
	v_readlane_b32 s22, v10, 52
	v_readlane_b32 s23, v8, 52
	v_fmac_f32_e32 v16, s20, v116
	v_fmac_f32_e32 v17, s21, v116
	v_fmac_f32_e32 v18, s22, v116
	v_fmac_f32_e32 v19, s23, v116
	global_load_dword v116, v[6:7], off
	v_lshl_add_u64 v[6:7], v[6:7], 0, s[12:13]
	s_waitcnt vmcnt(55)
	v_readlane_b32 s20, v14, 53
	v_readlane_b32 s21, v12, 53
	v_readlane_b32 s22, v10, 53
	v_readlane_b32 s23, v8, 53
	v_fmac_f32_e32 v16, s20, v117
	v_fmac_f32_e32 v17, s21, v117
	v_fmac_f32_e32 v18, s22, v117
	v_fmac_f32_e32 v19, s23, v117
	global_load_dword v117, v[6:7], off
	v_lshl_add_u64 v[6:7], v[6:7], 0, s[12:13]
	s_waitcnt vmcnt(55)
	v_readlane_b32 s20, v14, 54
	v_readlane_b32 s21, v12, 54
	v_readlane_b32 s22, v10, 54
	v_readlane_b32 s23, v8, 54
	v_fmac_f32_e32 v16, s20, v118
	v_fmac_f32_e32 v17, s21, v118
	v_fmac_f32_e32 v18, s22, v118
	v_fmac_f32_e32 v19, s23, v118
	global_load_dword v118, v[6:7], off
	v_lshl_add_u64 v[6:7], v[6:7], 0, s[12:13]
	s_waitcnt vmcnt(55)
	v_readlane_b32 s20, v14, 55
	v_readlane_b32 s21, v12, 55
	v_readlane_b32 s22, v10, 55
	v_readlane_b32 s23, v8, 55
	v_fmac_f32_e32 v16, s20, v119
	v_fmac_f32_e32 v17, s21, v119
	v_fmac_f32_e32 v18, s22, v119
	v_fmac_f32_e32 v19, s23, v119
	global_load_dword v119, v[6:7], off
	v_lshl_add_u64 v[6:7], v[6:7], 0, s[12:13]
	s_waitcnt vmcnt(55)
	v_readlane_b32 s20, v14, 56
	v_readlane_b32 s21, v12, 56
	v_readlane_b32 s22, v10, 56
	v_readlane_b32 s23, v8, 56
	v_fmac_f32_e32 v16, s20, v64
	v_fmac_f32_e32 v17, s21, v64
	v_fmac_f32_e32 v18, s22, v64
	v_fmac_f32_e32 v19, s23, v64
	global_load_dword v64, v[6:7], off
	v_lshl_add_u64 v[6:7], v[6:7], 0, s[12:13]
	s_waitcnt vmcnt(55)
	v_readlane_b32 s20, v14, 57
	v_readlane_b32 s21, v12, 57
	v_readlane_b32 s22, v10, 57
	v_readlane_b32 s23, v8, 57
	v_fmac_f32_e32 v16, s20, v65
	v_fmac_f32_e32 v17, s21, v65
	v_fmac_f32_e32 v18, s22, v65
	v_fmac_f32_e32 v19, s23, v65
	global_load_dword v65, v[6:7], off
	v_lshl_add_u64 v[6:7], v[6:7], 0, s[12:13]
	s_waitcnt vmcnt(55)
	v_readlane_b32 s20, v14, 58
	v_readlane_b32 s21, v12, 58
	v_readlane_b32 s22, v10, 58
	v_readlane_b32 s23, v8, 58
	v_fmac_f32_e32 v16, s20, v66
	v_fmac_f32_e32 v17, s21, v66
	v_fmac_f32_e32 v18, s22, v66
	v_fmac_f32_e32 v19, s23, v66
	global_load_dword v66, v[6:7], off
	v_lshl_add_u64 v[6:7], v[6:7], 0, s[12:13]
	s_waitcnt vmcnt(55)
	v_readlane_b32 s20, v14, 59
	v_readlane_b32 s21, v12, 59
	v_readlane_b32 s22, v10, 59
	v_readlane_b32 s23, v8, 59
	v_fmac_f32_e32 v16, s20, v67
	v_fmac_f32_e32 v17, s21, v67
	v_fmac_f32_e32 v18, s22, v67
	v_fmac_f32_e32 v19, s23, v67
	global_load_dword v67, v[6:7], off
	v_lshl_add_u64 v[6:7], v[6:7], 0, s[12:13]
	s_waitcnt vmcnt(55)
	v_readlane_b32 s20, v14, 60
	v_readlane_b32 s21, v12, 60
	v_readlane_b32 s22, v10, 60
	v_readlane_b32 s23, v8, 60
	v_fmac_f32_e32 v16, s20, v68
	v_fmac_f32_e32 v17, s21, v68
	v_fmac_f32_e32 v18, s22, v68
	v_fmac_f32_e32 v19, s23, v68
	global_load_dword v68, v[6:7], off
	v_lshl_add_u64 v[6:7], v[6:7], 0, s[12:13]
	s_waitcnt vmcnt(55)
	v_readlane_b32 s20, v14, 61
	v_readlane_b32 s21, v12, 61
	v_readlane_b32 s22, v10, 61
	v_readlane_b32 s23, v8, 61
	v_fmac_f32_e32 v16, s20, v69
	v_fmac_f32_e32 v17, s21, v69
	v_fmac_f32_e32 v18, s22, v69
	v_fmac_f32_e32 v19, s23, v69
	global_load_dword v69, v[6:7], off
	v_lshl_add_u64 v[6:7], v[6:7], 0, s[12:13]
	s_waitcnt vmcnt(55)
	v_readlane_b32 s20, v14, 62
	v_readlane_b32 s21, v12, 62
	v_readlane_b32 s22, v10, 62
	v_readlane_b32 s23, v8, 62
	v_fmac_f32_e32 v16, s20, v70
	v_fmac_f32_e32 v17, s21, v70
	v_fmac_f32_e32 v18, s22, v70
	v_fmac_f32_e32 v19, s23, v70
	global_load_dword v70, v[6:7], off
	v_lshl_add_u64 v[6:7], v[6:7], 0, s[12:13]
	s_waitcnt vmcnt(55)
	v_readlane_b32 s20, v14, 63
	v_readlane_b32 s21, v12, 63
	v_readlane_b32 s22, v10, 63
	v_readlane_b32 s23, v8, 63
	v_fmac_f32_e32 v16, s20, v71
	v_fmac_f32_e32 v17, s21, v71
	v_fmac_f32_e32 v18, s22, v71
	v_fmac_f32_e32 v19, s23, v71
	global_load_dword v71, v[6:7], off
	v_lshl_add_u64 v[6:7], v[6:7], 0, s[12:13]
	s_waitcnt vmcnt(55)
	v_readlane_b32 s20, v15, 0
	v_readlane_b32 s21, v13, 0
	v_readlane_b32 s22, v11, 0
	v_readlane_b32 s23, v9, 0
	v_fmac_f32_e32 v16, s20, v72
	v_fmac_f32_e32 v17, s21, v72
	v_fmac_f32_e32 v18, s22, v72
	v_fmac_f32_e32 v19, s23, v72
	global_load_dword v72, v[6:7], off
	v_lshl_add_u64 v[6:7], v[6:7], 0, s[12:13]
	s_waitcnt vmcnt(55)
	v_readlane_b32 s20, v15, 1
	v_readlane_b32 s21, v13, 1
	v_readlane_b32 s22, v11, 1
	v_readlane_b32 s23, v9, 1
	v_fmac_f32_e32 v16, s20, v73
	v_fmac_f32_e32 v17, s21, v73
	v_fmac_f32_e32 v18, s22, v73
	v_fmac_f32_e32 v19, s23, v73
	global_load_dword v73, v[6:7], off
	v_lshl_add_u64 v[6:7], v[6:7], 0, s[12:13]
	s_waitcnt vmcnt(55)
	v_readlane_b32 s20, v15, 2
	v_readlane_b32 s21, v13, 2
	v_readlane_b32 s22, v11, 2
	v_readlane_b32 s23, v9, 2
	v_fmac_f32_e32 v16, s20, v74
	v_fmac_f32_e32 v17, s21, v74
	v_fmac_f32_e32 v18, s22, v74
	v_fmac_f32_e32 v19, s23, v74
	global_load_dword v74, v[6:7], off
	v_lshl_add_u64 v[6:7], v[6:7], 0, s[12:13]
	s_waitcnt vmcnt(55)
	v_readlane_b32 s20, v15, 3
	v_readlane_b32 s21, v13, 3
	v_readlane_b32 s22, v11, 3
	v_readlane_b32 s23, v9, 3
	v_fmac_f32_e32 v16, s20, v75
	v_fmac_f32_e32 v17, s21, v75
	v_fmac_f32_e32 v18, s22, v75
	v_fmac_f32_e32 v19, s23, v75
	global_load_dword v75, v[6:7], off
	v_lshl_add_u64 v[6:7], v[6:7], 0, s[12:13]
	s_waitcnt vmcnt(55)
	v_readlane_b32 s20, v15, 4
	v_readlane_b32 s21, v13, 4
	v_readlane_b32 s22, v11, 4
	v_readlane_b32 s23, v9, 4
	v_fmac_f32_e32 v16, s20, v76
	v_fmac_f32_e32 v17, s21, v76
	v_fmac_f32_e32 v18, s22, v76
	v_fmac_f32_e32 v19, s23, v76
	global_load_dword v76, v[6:7], off
	v_lshl_add_u64 v[6:7], v[6:7], 0, s[12:13]
	s_waitcnt vmcnt(55)
	v_readlane_b32 s20, v15, 5
	v_readlane_b32 s21, v13, 5
	v_readlane_b32 s22, v11, 5
	v_readlane_b32 s23, v9, 5
	v_fmac_f32_e32 v16, s20, v77
	v_fmac_f32_e32 v17, s21, v77
	v_fmac_f32_e32 v18, s22, v77
	v_fmac_f32_e32 v19, s23, v77
	global_load_dword v77, v[6:7], off
	v_lshl_add_u64 v[6:7], v[6:7], 0, s[12:13]
	s_waitcnt vmcnt(55)
	v_readlane_b32 s20, v15, 6
	v_readlane_b32 s21, v13, 6
	v_readlane_b32 s22, v11, 6
	v_readlane_b32 s23, v9, 6
	v_fmac_f32_e32 v16, s20, v78
	v_fmac_f32_e32 v17, s21, v78
	v_fmac_f32_e32 v18, s22, v78
	v_fmac_f32_e32 v19, s23, v78
	global_load_dword v78, v[6:7], off
	v_lshl_add_u64 v[6:7], v[6:7], 0, s[12:13]
	s_waitcnt vmcnt(55)
	v_readlane_b32 s20, v15, 7
	v_readlane_b32 s21, v13, 7
	v_readlane_b32 s22, v11, 7
	v_readlane_b32 s23, v9, 7
	v_fmac_f32_e32 v16, s20, v79
	v_fmac_f32_e32 v17, s21, v79
	v_fmac_f32_e32 v18, s22, v79
	v_fmac_f32_e32 v19, s23, v79
	global_load_dword v79, v[6:7], off
	s_waitcnt vmcnt(55)
	v_readlane_b32 s20, v15, 8
	v_readlane_b32 s21, v13, 8
	v_readlane_b32 s22, v11, 8
	v_readlane_b32 s23, v9, 8
	v_fmac_f32_e32 v16, s20, v80
	v_fmac_f32_e32 v17, s21, v80
	v_fmac_f32_e32 v18, s22, v80
	v_fmac_f32_e32 v19, s23, v80
	s_waitcnt vmcnt(54)
	v_readlane_b32 s20, v15, 9
	v_readlane_b32 s21, v13, 9
	v_readlane_b32 s22, v11, 9
	v_readlane_b32 s23, v9, 9
	v_fmac_f32_e32 v16, s20, v81
	v_fmac_f32_e32 v17, s21, v81
	v_fmac_f32_e32 v18, s22, v81
	v_fmac_f32_e32 v19, s23, v81
	s_waitcnt vmcnt(53)
	v_readlane_b32 s20, v15, 10
	v_readlane_b32 s21, v13, 10
	v_readlane_b32 s22, v11, 10
	v_readlane_b32 s23, v9, 10
	v_fmac_f32_e32 v16, s20, v82
	v_fmac_f32_e32 v17, s21, v82
	v_fmac_f32_e32 v18, s22, v82
	v_fmac_f32_e32 v19, s23, v82
	s_waitcnt vmcnt(52)
	v_readlane_b32 s20, v15, 11
	v_readlane_b32 s21, v13, 11
	v_readlane_b32 s22, v11, 11
	v_readlane_b32 s23, v9, 11
	v_fmac_f32_e32 v16, s20, v83
	v_fmac_f32_e32 v17, s21, v83
	v_fmac_f32_e32 v18, s22, v83
	v_fmac_f32_e32 v19, s23, v83
	s_waitcnt vmcnt(51)
	v_readlane_b32 s20, v15, 12
	v_readlane_b32 s21, v13, 12
	v_readlane_b32 s22, v11, 12
	v_readlane_b32 s23, v9, 12
	v_fmac_f32_e32 v16, s20, v84
	v_fmac_f32_e32 v17, s21, v84
	v_fmac_f32_e32 v18, s22, v84
	v_fmac_f32_e32 v19, s23, v84
	s_waitcnt vmcnt(50)
	v_readlane_b32 s20, v15, 13
	v_readlane_b32 s21, v13, 13
	v_readlane_b32 s22, v11, 13
	v_readlane_b32 s23, v9, 13
	v_fmac_f32_e32 v16, s20, v85
	v_fmac_f32_e32 v17, s21, v85
	v_fmac_f32_e32 v18, s22, v85
	v_fmac_f32_e32 v19, s23, v85
	s_waitcnt vmcnt(49)
	v_readlane_b32 s20, v15, 14
	v_readlane_b32 s21, v13, 14
	v_readlane_b32 s22, v11, 14
	v_readlane_b32 s23, v9, 14
	v_fmac_f32_e32 v16, s20, v86
	v_fmac_f32_e32 v17, s21, v86
	v_fmac_f32_e32 v18, s22, v86
	v_fmac_f32_e32 v19, s23, v86
	s_waitcnt vmcnt(48)
	v_readlane_b32 s20, v15, 15
	v_readlane_b32 s21, v13, 15
	v_readlane_b32 s22, v11, 15
	v_readlane_b32 s23, v9, 15
	v_fmac_f32_e32 v16, s20, v87
	v_fmac_f32_e32 v17, s21, v87
	v_fmac_f32_e32 v18, s22, v87
	v_fmac_f32_e32 v19, s23, v87
	s_waitcnt vmcnt(47)
	v_readlane_b32 s20, v15, 16
	v_readlane_b32 s21, v13, 16
	v_readlane_b32 s22, v11, 16
	v_readlane_b32 s23, v9, 16
	v_fmac_f32_e32 v16, s20, v88
	v_fmac_f32_e32 v17, s21, v88
	v_fmac_f32_e32 v18, s22, v88
	v_fmac_f32_e32 v19, s23, v88
	s_waitcnt vmcnt(46)
	v_readlane_b32 s20, v15, 17
	v_readlane_b32 s21, v13, 17
	v_readlane_b32 s22, v11, 17
	v_readlane_b32 s23, v9, 17
	v_fmac_f32_e32 v16, s20, v89
	v_fmac_f32_e32 v17, s21, v89
	v_fmac_f32_e32 v18, s22, v89
	v_fmac_f32_e32 v19, s23, v89
	s_waitcnt vmcnt(45)
	v_readlane_b32 s20, v15, 18
	v_readlane_b32 s21, v13, 18
	v_readlane_b32 s22, v11, 18
	v_readlane_b32 s23, v9, 18
	v_fmac_f32_e32 v16, s20, v90
	v_fmac_f32_e32 v17, s21, v90
	v_fmac_f32_e32 v18, s22, v90
	v_fmac_f32_e32 v19, s23, v90
	s_waitcnt vmcnt(44)
	v_readlane_b32 s20, v15, 19
	v_readlane_b32 s21, v13, 19
	v_readlane_b32 s22, v11, 19
	v_readlane_b32 s23, v9, 19
	v_fmac_f32_e32 v16, s20, v91
	v_fmac_f32_e32 v17, s21, v91
	v_fmac_f32_e32 v18, s22, v91
	v_fmac_f32_e32 v19, s23, v91
	s_waitcnt vmcnt(43)
	v_readlane_b32 s20, v15, 20
	v_readlane_b32 s21, v13, 20
	v_readlane_b32 s22, v11, 20
	v_readlane_b32 s23, v9, 20
	v_fmac_f32_e32 v16, s20, v92
	v_fmac_f32_e32 v17, s21, v92
	v_fmac_f32_e32 v18, s22, v92
	v_fmac_f32_e32 v19, s23, v92
	s_waitcnt vmcnt(42)
	v_readlane_b32 s20, v15, 21
	v_readlane_b32 s21, v13, 21
	v_readlane_b32 s22, v11, 21
	v_readlane_b32 s23, v9, 21
	v_fmac_f32_e32 v16, s20, v93
	v_fmac_f32_e32 v17, s21, v93
	v_fmac_f32_e32 v18, s22, v93
	v_fmac_f32_e32 v19, s23, v93
	s_waitcnt vmcnt(41)
	v_readlane_b32 s20, v15, 22
	v_readlane_b32 s21, v13, 22
	v_readlane_b32 s22, v11, 22
	v_readlane_b32 s23, v9, 22
	v_fmac_f32_e32 v16, s20, v94
	v_fmac_f32_e32 v17, s21, v94
	v_fmac_f32_e32 v18, s22, v94
	v_fmac_f32_e32 v19, s23, v94
	s_waitcnt vmcnt(40)
	v_readlane_b32 s20, v15, 23
	v_readlane_b32 s21, v13, 23
	v_readlane_b32 s22, v11, 23
	v_readlane_b32 s23, v9, 23
	v_fmac_f32_e32 v16, s20, v95
	v_fmac_f32_e32 v17, s21, v95
	v_fmac_f32_e32 v18, s22, v95
	v_fmac_f32_e32 v19, s23, v95
	s_waitcnt vmcnt(39)
	v_readlane_b32 s20, v15, 24
	v_readlane_b32 s21, v13, 24
	v_readlane_b32 s22, v11, 24
	v_readlane_b32 s23, v9, 24
	v_fmac_f32_e32 v16, s20, v96
	v_fmac_f32_e32 v17, s21, v96
	v_fmac_f32_e32 v18, s22, v96
	v_fmac_f32_e32 v19, s23, v96
	s_waitcnt vmcnt(38)
	v_readlane_b32 s20, v15, 25
	v_readlane_b32 s21, v13, 25
	v_readlane_b32 s22, v11, 25
	v_readlane_b32 s23, v9, 25
	v_fmac_f32_e32 v16, s20, v97
	v_fmac_f32_e32 v17, s21, v97
	v_fmac_f32_e32 v18, s22, v97
	v_fmac_f32_e32 v19, s23, v97
	s_waitcnt vmcnt(37)
	v_readlane_b32 s20, v15, 26
	v_readlane_b32 s21, v13, 26
	v_readlane_b32 s22, v11, 26
	v_readlane_b32 s23, v9, 26
	v_fmac_f32_e32 v16, s20, v98
	v_fmac_f32_e32 v17, s21, v98
	v_fmac_f32_e32 v18, s22, v98
	v_fmac_f32_e32 v19, s23, v98
	s_waitcnt vmcnt(36)
	v_readlane_b32 s20, v15, 27
	v_readlane_b32 s21, v13, 27
	v_readlane_b32 s22, v11, 27
	v_readlane_b32 s23, v9, 27
	v_fmac_f32_e32 v16, s20, v99
	v_fmac_f32_e32 v17, s21, v99
	v_fmac_f32_e32 v18, s22, v99
	v_fmac_f32_e32 v19, s23, v99
	s_waitcnt vmcnt(35)
	v_readlane_b32 s20, v15, 28
	v_readlane_b32 s21, v13, 28
	v_readlane_b32 s22, v11, 28
	v_readlane_b32 s23, v9, 28
	v_fmac_f32_e32 v16, s20, v100
	v_fmac_f32_e32 v17, s21, v100
	v_fmac_f32_e32 v18, s22, v100
	v_fmac_f32_e32 v19, s23, v100
	s_waitcnt vmcnt(34)
	v_readlane_b32 s20, v15, 29
	v_readlane_b32 s21, v13, 29
	v_readlane_b32 s22, v11, 29
	v_readlane_b32 s23, v9, 29
	v_fmac_f32_e32 v16, s20, v101
	v_fmac_f32_e32 v17, s21, v101
	v_fmac_f32_e32 v18, s22, v101
	v_fmac_f32_e32 v19, s23, v101
	s_waitcnt vmcnt(33)
	v_readlane_b32 s20, v15, 30
	v_readlane_b32 s21, v13, 30
	v_readlane_b32 s22, v11, 30
	v_readlane_b32 s23, v9, 30
	v_fmac_f32_e32 v16, s20, v102
	v_fmac_f32_e32 v17, s21, v102
	v_fmac_f32_e32 v18, s22, v102
	v_fmac_f32_e32 v19, s23, v102
	s_waitcnt vmcnt(32)
	v_readlane_b32 s20, v15, 31
	v_readlane_b32 s21, v13, 31
	v_readlane_b32 s22, v11, 31
	v_readlane_b32 s23, v9, 31
	v_fmac_f32_e32 v16, s20, v103
	v_fmac_f32_e32 v17, s21, v103
	v_fmac_f32_e32 v18, s22, v103
	v_fmac_f32_e32 v19, s23, v103
	s_waitcnt vmcnt(31)
	v_readlane_b32 s20, v15, 32
	v_readlane_b32 s21, v13, 32
	v_readlane_b32 s22, v11, 32
	v_readlane_b32 s23, v9, 32
	v_fmac_f32_e32 v16, s20, v104
	v_fmac_f32_e32 v17, s21, v104
	v_fmac_f32_e32 v18, s22, v104
	v_fmac_f32_e32 v19, s23, v104
	s_waitcnt vmcnt(30)
	v_readlane_b32 s20, v15, 33
	v_readlane_b32 s21, v13, 33
	v_readlane_b32 s22, v11, 33
	v_readlane_b32 s23, v9, 33
	v_fmac_f32_e32 v16, s20, v105
	v_fmac_f32_e32 v17, s21, v105
	v_fmac_f32_e32 v18, s22, v105
	v_fmac_f32_e32 v19, s23, v105
	s_waitcnt vmcnt(29)
	v_readlane_b32 s20, v15, 34
	v_readlane_b32 s21, v13, 34
	v_readlane_b32 s22, v11, 34
	v_readlane_b32 s23, v9, 34
	v_fmac_f32_e32 v16, s20, v106
	v_fmac_f32_e32 v17, s21, v106
	v_fmac_f32_e32 v18, s22, v106
	v_fmac_f32_e32 v19, s23, v106
	s_waitcnt vmcnt(28)
	v_readlane_b32 s20, v15, 35
	v_readlane_b32 s21, v13, 35
	v_readlane_b32 s22, v11, 35
	v_readlane_b32 s23, v9, 35
	v_fmac_f32_e32 v16, s20, v107
	v_fmac_f32_e32 v17, s21, v107
	v_fmac_f32_e32 v18, s22, v107
	v_fmac_f32_e32 v19, s23, v107
	s_waitcnt vmcnt(27)
	v_readlane_b32 s20, v15, 36
	v_readlane_b32 s21, v13, 36
	v_readlane_b32 s22, v11, 36
	v_readlane_b32 s23, v9, 36
	v_fmac_f32_e32 v16, s20, v108
	v_fmac_f32_e32 v17, s21, v108
	v_fmac_f32_e32 v18, s22, v108
	v_fmac_f32_e32 v19, s23, v108
	s_waitcnt vmcnt(26)
	v_readlane_b32 s20, v15, 37
	v_readlane_b32 s21, v13, 37
	v_readlane_b32 s22, v11, 37
	v_readlane_b32 s23, v9, 37
	v_fmac_f32_e32 v16, s20, v109
	v_fmac_f32_e32 v17, s21, v109
	v_fmac_f32_e32 v18, s22, v109
	v_fmac_f32_e32 v19, s23, v109
	s_waitcnt vmcnt(25)
	v_readlane_b32 s20, v15, 38
	v_readlane_b32 s21, v13, 38
	v_readlane_b32 s22, v11, 38
	v_readlane_b32 s23, v9, 38
	v_fmac_f32_e32 v16, s20, v110
	v_fmac_f32_e32 v17, s21, v110
	v_fmac_f32_e32 v18, s22, v110
	v_fmac_f32_e32 v19, s23, v110
	s_waitcnt vmcnt(24)
	v_readlane_b32 s20, v15, 39
	v_readlane_b32 s21, v13, 39
	v_readlane_b32 s22, v11, 39
	v_readlane_b32 s23, v9, 39
	v_fmac_f32_e32 v16, s20, v111
	v_fmac_f32_e32 v17, s21, v111
	v_fmac_f32_e32 v18, s22, v111
	v_fmac_f32_e32 v19, s23, v111
	s_waitcnt vmcnt(23)
	v_readlane_b32 s20, v15, 40
	v_readlane_b32 s21, v13, 40
	v_readlane_b32 s22, v11, 40
	v_readlane_b32 s23, v9, 40
	v_fmac_f32_e32 v16, s20, v112
	v_fmac_f32_e32 v17, s21, v112
	v_fmac_f32_e32 v18, s22, v112
	v_fmac_f32_e32 v19, s23, v112
	s_waitcnt vmcnt(22)
	v_readlane_b32 s20, v15, 41
	v_readlane_b32 s21, v13, 41
	v_readlane_b32 s22, v11, 41
	v_readlane_b32 s23, v9, 41
	v_fmac_f32_e32 v16, s20, v113
	v_fmac_f32_e32 v17, s21, v113
	v_fmac_f32_e32 v18, s22, v113
	v_fmac_f32_e32 v19, s23, v113
	s_waitcnt vmcnt(21)
	v_readlane_b32 s20, v15, 42
	v_readlane_b32 s21, v13, 42
	v_readlane_b32 s22, v11, 42
	v_readlane_b32 s23, v9, 42
	v_fmac_f32_e32 v16, s20, v114
	v_fmac_f32_e32 v17, s21, v114
	v_fmac_f32_e32 v18, s22, v114
	v_fmac_f32_e32 v19, s23, v114
	s_waitcnt vmcnt(20)
	v_readlane_b32 s20, v15, 43
	v_readlane_b32 s21, v13, 43
	v_readlane_b32 s22, v11, 43
	v_readlane_b32 s23, v9, 43
	v_fmac_f32_e32 v16, s20, v115
	v_fmac_f32_e32 v17, s21, v115
	v_fmac_f32_e32 v18, s22, v115
	v_fmac_f32_e32 v19, s23, v115
	s_waitcnt vmcnt(19)
	v_readlane_b32 s20, v15, 44
	v_readlane_b32 s21, v13, 44
	v_readlane_b32 s22, v11, 44
	v_readlane_b32 s23, v9, 44
	v_fmac_f32_e32 v16, s20, v116
	v_fmac_f32_e32 v17, s21, v116
	v_fmac_f32_e32 v18, s22, v116
	v_fmac_f32_e32 v19, s23, v116
	s_waitcnt vmcnt(18)
	v_readlane_b32 s20, v15, 45
	v_readlane_b32 s21, v13, 45
	v_readlane_b32 s22, v11, 45
	v_readlane_b32 s23, v9, 45
	v_fmac_f32_e32 v16, s20, v117
	v_fmac_f32_e32 v17, s21, v117
	v_fmac_f32_e32 v18, s22, v117
	v_fmac_f32_e32 v19, s23, v117
	s_waitcnt vmcnt(17)
	v_readlane_b32 s20, v15, 46
	v_readlane_b32 s21, v13, 46
	v_readlane_b32 s22, v11, 46
	v_readlane_b32 s23, v9, 46
	v_fmac_f32_e32 v16, s20, v118
	v_fmac_f32_e32 v17, s21, v118
	v_fmac_f32_e32 v18, s22, v118
	v_fmac_f32_e32 v19, s23, v118
	s_waitcnt vmcnt(16)
	v_readlane_b32 s20, v15, 47
	v_readlane_b32 s21, v13, 47
	v_readlane_b32 s22, v11, 47
	v_readlane_b32 s23, v9, 47
	v_fmac_f32_e32 v16, s20, v119
	v_fmac_f32_e32 v17, s21, v119
	v_fmac_f32_e32 v18, s22, v119
	v_fmac_f32_e32 v19, s23, v119
	s_waitcnt vmcnt(15)
	v_readlane_b32 s20, v15, 48
	v_readlane_b32 s21, v13, 48
	v_readlane_b32 s22, v11, 48
	v_readlane_b32 s23, v9, 48
	v_fmac_f32_e32 v16, s20, v64
	v_fmac_f32_e32 v17, s21, v64
	v_fmac_f32_e32 v18, s22, v64
	v_fmac_f32_e32 v19, s23, v64
	s_waitcnt vmcnt(14)
	v_readlane_b32 s20, v15, 49
	v_readlane_b32 s21, v13, 49
	v_readlane_b32 s22, v11, 49
	v_readlane_b32 s23, v9, 49
	v_fmac_f32_e32 v16, s20, v65
	v_fmac_f32_e32 v17, s21, v65
	v_fmac_f32_e32 v18, s22, v65
	v_fmac_f32_e32 v19, s23, v65
	s_waitcnt vmcnt(13)
	v_readlane_b32 s20, v15, 50
	v_readlane_b32 s21, v13, 50
	v_readlane_b32 s22, v11, 50
	v_readlane_b32 s23, v9, 50
	v_fmac_f32_e32 v16, s20, v66
	v_fmac_f32_e32 v17, s21, v66
	v_fmac_f32_e32 v18, s22, v66
	v_fmac_f32_e32 v19, s23, v66
	s_waitcnt vmcnt(12)
	v_readlane_b32 s20, v15, 51
	v_readlane_b32 s21, v13, 51
	v_readlane_b32 s22, v11, 51
	v_readlane_b32 s23, v9, 51
	v_fmac_f32_e32 v16, s20, v67
	v_fmac_f32_e32 v17, s21, v67
	v_fmac_f32_e32 v18, s22, v67
	v_fmac_f32_e32 v19, s23, v67
	s_waitcnt vmcnt(11)
	v_readlane_b32 s20, v15, 52
	v_readlane_b32 s21, v13, 52
	v_readlane_b32 s22, v11, 52
	v_readlane_b32 s23, v9, 52
	v_fmac_f32_e32 v16, s20, v68
	v_fmac_f32_e32 v17, s21, v68
	v_fmac_f32_e32 v18, s22, v68
	v_fmac_f32_e32 v19, s23, v68
	s_waitcnt vmcnt(10)
	v_readlane_b32 s20, v15, 53
	v_readlane_b32 s21, v13, 53
	v_readlane_b32 s22, v11, 53
	v_readlane_b32 s23, v9, 53
	v_fmac_f32_e32 v16, s20, v69
	v_fmac_f32_e32 v17, s21, v69
	v_fmac_f32_e32 v18, s22, v69
	v_fmac_f32_e32 v19, s23, v69
	s_waitcnt vmcnt(9)
	v_readlane_b32 s20, v15, 54
	v_readlane_b32 s21, v13, 54
	v_readlane_b32 s22, v11, 54
	v_readlane_b32 s23, v9, 54
	v_fmac_f32_e32 v16, s20, v70
	v_fmac_f32_e32 v17, s21, v70
	v_fmac_f32_e32 v18, s22, v70
	v_fmac_f32_e32 v19, s23, v70
	s_waitcnt vmcnt(8)
	v_readlane_b32 s20, v15, 55
	v_readlane_b32 s21, v13, 55
	v_readlane_b32 s22, v11, 55
	v_readlane_b32 s23, v9, 55
	v_fmac_f32_e32 v16, s20, v71
	v_fmac_f32_e32 v17, s21, v71
	v_fmac_f32_e32 v18, s22, v71
	v_fmac_f32_e32 v19, s23, v71
	s_waitcnt vmcnt(7)
	v_readlane_b32 s20, v15, 56
	v_readlane_b32 s21, v13, 56
	v_readlane_b32 s22, v11, 56
	v_readlane_b32 s23, v9, 56
	v_fmac_f32_e32 v16, s20, v72
	v_fmac_f32_e32 v17, s21, v72
	v_fmac_f32_e32 v18, s22, v72
	v_fmac_f32_e32 v19, s23, v72
	s_waitcnt vmcnt(6)
	v_readlane_b32 s20, v15, 57
	v_readlane_b32 s21, v13, 57
	v_readlane_b32 s22, v11, 57
	v_readlane_b32 s23, v9, 57
	v_fmac_f32_e32 v16, s20, v73
	v_fmac_f32_e32 v17, s21, v73
	v_fmac_f32_e32 v18, s22, v73
	v_fmac_f32_e32 v19, s23, v73
	s_waitcnt vmcnt(5)
	v_readlane_b32 s20, v15, 58
	v_readlane_b32 s21, v13, 58
	v_readlane_b32 s22, v11, 58
	v_readlane_b32 s23, v9, 58
	v_fmac_f32_e32 v16, s20, v74
	v_fmac_f32_e32 v17, s21, v74
	v_fmac_f32_e32 v18, s22, v74
	v_fmac_f32_e32 v19, s23, v74
	s_waitcnt vmcnt(4)
	v_readlane_b32 s20, v15, 59
	v_readlane_b32 s21, v13, 59
	v_readlane_b32 s22, v11, 59
	v_readlane_b32 s23, v9, 59
	v_fmac_f32_e32 v16, s20, v75
	v_fmac_f32_e32 v17, s21, v75
	v_fmac_f32_e32 v18, s22, v75
	v_fmac_f32_e32 v19, s23, v75
	s_waitcnt vmcnt(3)
	v_readlane_b32 s20, v15, 60
	v_readlane_b32 s21, v13, 60
	v_readlane_b32 s22, v11, 60
	v_readlane_b32 s23, v9, 60
	v_fmac_f32_e32 v16, s20, v76
	v_fmac_f32_e32 v17, s21, v76
	v_fmac_f32_e32 v18, s22, v76
	v_fmac_f32_e32 v19, s23, v76
	s_waitcnt vmcnt(2)
	v_readlane_b32 s20, v15, 61
	v_readlane_b32 s21, v13, 61
	v_readlane_b32 s22, v11, 61
	v_readlane_b32 s23, v9, 61
	v_fmac_f32_e32 v16, s20, v77
	v_fmac_f32_e32 v17, s21, v77
	v_fmac_f32_e32 v18, s22, v77
	v_fmac_f32_e32 v19, s23, v77
	s_waitcnt vmcnt(1)
	v_readlane_b32 s20, v15, 62
	v_readlane_b32 s21, v13, 62
	v_readlane_b32 s22, v11, 62
	v_readlane_b32 s23, v9, 62
	v_fmac_f32_e32 v16, s20, v78
	v_fmac_f32_e32 v17, s21, v78
	v_fmac_f32_e32 v18, s22, v78
	v_fmac_f32_e32 v19, s23, v78
	s_waitcnt vmcnt(0)
	v_readlane_b32 s20, v15, 63
	v_readlane_b32 s21, v13, 63
	v_readlane_b32 s22, v11, 63
	v_readlane_b32 s23, v9, 63
	v_fmac_f32_e32 v16, s20, v79
	v_fmac_f32_e32 v17, s21, v79
	v_fmac_f32_e32 v18, s22, v79
	v_fmac_f32_e32 v19, s23, v79
	s_movk_i32 s0, 0x100
	v_add_u32_e32 v1, s1, v4
	v_cmp_gt_i32_e32 vcc, s0, v42
	ds_write2st64_b32 v1, v16, v17 offset0:64 offset1:65
	ds_write2st64_b32 v1, v18, v19 offset0:66 offset1:67
	s_waitcnt lgkmcnt(0)
	s_barrier
	s_and_saveexec_b64 s[0:1], vcc
	s_cbranch_execz .LBB0_18
	s_load_dwordx2 s[6:7], s[8:9], 0x18
	v_or_b32_e32 v6, v54, v2
	v_ashrrev_i32_e32 v7, 31, v6
	v_and_b32_e32 v8, 0x3fffffc0, v42
	v_ashrrev_i32_e32 v9, 6, v42
	s_waitcnt lgkmcnt(0)
	v_lshl_add_u64 v[6:7], v[6:7], 2, s[6:7]
	global_load_dword v1, v[6:7], off
	v_mov_b64_e32 v[6:7], s[18:19]
	v_lshlrev_b32_e32 v8, 2, v8
	v_mad_i64_i32 v[6:7], s[4:5], v9, s4, v[6:7]
	v_add3_u32 v12, 0, v8, v4
	v_lshl_add_u64 v[2:3], v[2:3], 2, v[6:7]
	ds_read2st64_b32 v[6:7], v12 offset0:64 offset1:68
	ds_read2st64_b32 v[8:9], v12 offset0:72 offset1:76
	ds_read2st64_b32 v[10:11], v12 offset0:80 offset1:84
	ds_read2st64_b32 v[12:13], v12 offset0:88 offset1:92
	v_lshl_add_u64 v[2:3], v[2:3], 0, v[4:5]
	v_add_co_u32_e32 v2, vcc, 0x100000, v2
	s_waitcnt vmcnt(0) lgkmcnt(3)
	v_add_f32_e32 v1, v1, v6
	v_add_f32_e32 v1, v1, v7
	s_waitcnt lgkmcnt(2)
	v_add_f32_e32 v1, v1, v8
	v_add_f32_e32 v1, v1, v9
	s_waitcnt lgkmcnt(1)
	v_add_f32_e32 v1, v1, v10
	v_add_f32_e32 v1, v1, v11
	s_waitcnt lgkmcnt(0)
	v_add_f32_e32 v1, v1, v12
	v_add_f32_e32 v1, v1, v13
	v_addc_co_u32_e32 v3, vcc, 0, v3, vcc
	flat_store_dword v[2:3], v1
